# attention loop: deferred V-tile DMA issued after the QK block (next to the K DMA) instead of at the half-step top
# speedup vs baseline: 1.0670x; 1.0023x over previous
.LBB0_389:
	ds_read_b128 v[98:101], v214 offset:49152
	ds_read_b128 v[102:105], v214 offset:49280
	ds_read_b128 v[106:109], v214 offset:57344
	ds_read_b128 v[110:113], v214 offset:57472
	ds_read_b128 v[178:181], v215 offset:49152
	ds_read_b128 v[184:187], v215 offset:49280
	ds_read_b128 v[188:191], v215 offset:57344
	ds_read_b128 v[226:229], v215 offset:57472
	s_waitcnt lgkmcnt(7)
	v_mfma_f32_32x32x16_bf16 v[50:65], v[98:101], v[158:161], v[50:65]
	ds_read_b128 v[98:101], v216 offset:49152
	ds_read_b128 v[230:233], v216 offset:49280
	ds_read_b128 v[234:237], v216 offset:57344
	ds_read_b128 v[238:241], v216 offset:57472
	ds_read_b128 v[242:245], v217 offset:49152
	ds_read_b128 v[246:249], v217 offset:49280
	ds_read_b128 v[250:253], v217 offset:57344
	ds_read_b128 v[192:195], v217 offset:57472
	v_exp_f32_e32 v128, v128
	v_exp_f32_e32 v129, v129
	v_exp_f32_e32 v126, v126
	v_exp_f32_e32 v127, v127
	v_exp_f32_e32 v124, v124
	v_exp_f32_e32 v125, v125
	s_waitcnt lgkmcnt(11)
	v_mfma_f32_32x32x16_bf16 v[50:65], v[178:181], v[154:157], v[50:65]
	v_exp_f32_e32 v122, v122
	v_exp_f32_e32 v116, v116
	v_exp_f32_e32 v117, v117
	v_exp_f32_e32 v114, v114
	v_exp_f32_e32 v115, v115
	v_cvt_pk_bf16_f32 v178, v175, v177
	v_cvt_pk_bf16_f32 v179, v173, v176
	s_waitcnt lgkmcnt(7)
	v_mfma_f32_32x32x16_bf16 v[50:65], v[98:101], v[150:153], v[50:65]
	v_exp_f32_e32 v101, v118
	v_exp_f32_e32 v118, v119
	v_add_f32_e32 v119, 0, v175
	v_add_f32_e32 v119, v177, v119
	v_add_f32_e32 v119, v173, v119
	v_add_f32_e32 v119, v176, v119
	v_add_f32_e32 v119, v171, v119
	s_waitcnt lgkmcnt(3)
	v_mfma_f32_32x32x16_bf16 v[50:65], v[242:245], v[146:149], v[50:65]
	v_exp_f32_e32 v98, v123
	v_exp_f32_e32 v99, v120
	v_exp_f32_e32 v100, v121
	v_cvt_pk_bf16_f32 v180, v171, v174
	v_cvt_pk_bf16_f32 v181, v170, v172
	s_nop 0
	v_permlane32_swap_b32_e32 v178, v180
	v_mfma_f32_32x32x16_bf16 v[50:65], v[102:105], v[142:145], v[50:65]
	v_add_f32_e32 v102, v174, v119
	v_add_f32_e32 v102, v170, v102
	v_add_f32_e32 v102, v172, v102
	v_add_f32_e32 v102, v164, v102
	v_add_f32_e32 v102, v167, v102
	v_add_f32_e32 v102, v163, v102
	v_add_f32_e32 v102, v165, v102
	v_mfma_f32_32x32x16_bf16 v[50:65], v[184:187], v[138:141], v[50:65]
	v_add_f32_e32 v102, v162, v102
	v_add_f32_e32 v102, v169, v102
	v_add_f32_e32 v102, v166, v102
	v_add_f32_e32 v102, v168, v102
	v_add_f32_e32 v102, v128, v102
	v_add_f32_e32 v102, v129, v102
	v_add_f32_e32 v102, v126, v102
	v_mfma_f32_32x32x16_bf16 v[50:65], v[230:233], v[134:137], v[50:65]
	v_add_f32_e32 v102, v127, v102
	v_add_f32_e32 v102, v124, v102
	v_add_f32_e32 v102, v125, v102
	v_add_f32_e32 v102, v122, v102
	v_add_f32_e32 v102, v98, v102
	v_add_f32_e32 v102, v99, v102
	v_add_f32_e32 v102, v100, v102
	s_waitcnt lgkmcnt(2)
	v_mfma_f32_32x32x16_bf16 v[50:65], v[246:249], v[130:133], v[50:65]
	v_add_f32_e32 v102, v101, v102
	v_add_f32_e32 v102, v118, v102
	v_add_f32_e32 v102, v116, v102
	v_add_f32_e32 v102, v117, v102
	v_add_f32_e32 v102, v114, v102
	v_add_f32_e32 v223, v115, v102
	v_mov_b32_e32 v224, v223
	s_nop 1
	v_permlane32_swap_b32_e32 v223, v224
	v_cvt_pk_bf16_f32 v184, v164, v167
	v_cvt_pk_bf16_f32 v185, v163, v165
	v_cvt_pk_bf16_f32 v186, v162, v169
	v_cvt_pk_bf16_f32 v187, v166, v168
	v_cvt_pk_bf16_f32 v230, v128, v129
	v_cvt_pk_bf16_f32 v231, v126, v127
	v_cvt_pk_bf16_f32 v232, v124, v125
	v_cvt_pk_bf16_f32 v233, v122, v98
	v_cvt_pk_bf16_f32 v242, v99, v100
	v_cvt_pk_bf16_f32 v243, v101, v118
	v_cvt_pk_bf16_f32 v244, v116, v117
	v_cvt_pk_bf16_f32 v245, v114, v115
	v_permlane32_swap_b32_e32 v179, v181
	v_permlane32_swap_b32_e32 v184, v186
	v_permlane32_swap_b32_e32 v185, v187
	v_permlane32_swap_b32_e32 v230, v232
	v_permlane32_swap_b32_e32 v231, v233
	v_permlane32_swap_b32_e32 v242, v244
	v_permlane32_swap_b32_e32 v243, v245
	v_mfma_f32_32x32x16_bf16 v[82:97], v[106:109], v[158:161], v[82:97]
	s_add_i32 s6, s38, 63
	v_mfma_f32_32x32x16_bf16 v[82:97], v[188:191], v[154:157], v[82:97]
	v_mfma_f32_32x32x16_bf16 v[82:97], v[234:237], v[150:153], v[82:97]
	s_waitcnt lgkmcnt(1)
	v_mfma_f32_32x32x16_bf16 v[82:97], v[250:253], v[146:149], v[82:97]
	v_mfma_f32_32x32x16_bf16 v[82:97], v[110:113], v[142:145], v[82:97]
	v_add_u32_e32 v110, 0x100, v221
	global_load_dwordx4 v[114:117], v110, s[52:53]
	global_load_dwordx4 v[118:121], v110, s[52:53] offset:32
	global_load_dwordx4 v[98:101], v110, s[52:53] offset:128
	global_load_dwordx4 v[102:105], v110, s[52:53] offset:160
	global_load_dwordx4 v[122:125], v110, s[52:53] offset:64
	global_load_dwordx4 v[126:129], v110, s[52:53] offset:96
	global_load_dwordx4 v[106:109], v110, s[52:53] offset:192
	s_nop 0
	global_load_dwordx4 v[110:113], v110, s[52:53] offset:224
	v_mfma_f32_32x32x16_bf16 v[82:97], v[226:229], v[138:141], v[82:97]
	v_mfma_f32_32x32x16_bf16 v[82:97], v[238:241], v[134:137], v[82:97]
	s_waitcnt lgkmcnt(0)
	v_mfma_f32_32x32x16_bf16 v[82:97], v[192:195], v[130:133], v[82:97]
	s_cmp_eq_u32 s33, 2
	s_cbranch_scc1 .Lat_od_nov
	s_add_i32 m0, s32, 0x4000
	v_add_u32_e32 v229, 0x80, v218
	global_load_lds_dwordx4 v218, s[100:101]
	s_add_i32 m0, s32, 0x4400
	s_nop 0
	global_load_lds_dwordx4 v229, s[100:101]
	s_sub_u32 s100, s100, 0x4000
	s_subb_u32 s101, s101, 0
.Lat_od_nov:
	s_add_i32 m0, s32, 0x8000
	v_xor_b32_e32 v229, 64, v219
	global_load_lds_dwordx4 v219, s[98:99]
	s_add_i32 m0, s32, 0x8400
	v_add_u32_e32 v229, 0x400, v229
	global_load_lds_dwordx4 v229, s[98:99]
	s_sub_u32 s98, s98, 0x4000
	s_subb_u32 s99, s99, 0
	ds_read_b64_tr_b16 v[188:189], v209 offset:0
	ds_read_b64_tr_b16 v[190:191], v209 offset:0x800
	ds_read_b64_tr_b16 v[192:193], v209 offset:0x1000
	ds_read_b64_tr_b16 v[194:195], v209 offset:0x1800
	ds_read_b64_tr_b16 v[234:235], v209 offset:0x2000
	ds_read_b64_tr_b16 v[236:237], v209 offset:0x2800
	ds_read_b64_tr_b16 v[238:239], v209 offset:0x3000
	ds_read_b64_tr_b16 v[240:241], v209 offset:0x3800
	s_nop 0
	s_waitcnt lgkmcnt(6)
	v_mfma_f32_32x32x16_bf16 v[66:81], v[178:181], v[188:191], v[66:81]
	ds_read_b64_tr_b16 v[188:189], v209 offset:0x200
	ds_read_b64_tr_b16 v[190:191], v209 offset:0xa00
	s_waitcnt lgkmcnt(6)
	v_mfma_f32_32x32x16_bf16 v[66:81], v[184:187], v[192:195], v[66:81]
	ds_read_b64_tr_b16 v[192:193], v209 offset:0x1200
	ds_read_b64_tr_b16 v[194:195], v209 offset:0x1a00
	s_waitcnt lgkmcnt(6)
	v_mfma_f32_32x32x16_bf16 v[66:81], v[230:233], v[234:237], v[66:81]
	ds_read_b64_tr_b16 v[234:235], v209 offset:0x2200
	ds_read_b64_tr_b16 v[236:237], v209 offset:0x2a00
	ds_read_b64_tr_b16 v[246:247], v209 offset:0x3200
	ds_read_b64_tr_b16 v[248:249], v209 offset:0x3a00
	s_waitcnt lgkmcnt(8)
	v_mfma_f32_32x32x16_bf16 v[66:81], v[242:245], v[238:241], v[66:81]
	s_waitcnt lgkmcnt(6)
	v_mfma_f32_32x32x16_bf16 v[34:49], v[178:181], v[188:191], v[34:49]
	ds_read_b64_tr_b16 v[188:189], v209 offset:0x400
	ds_read_b64_tr_b16 v[190:191], v209 offset:0xc00
	s_waitcnt lgkmcnt(6)
	v_mfma_f32_32x32x16_bf16 v[34:49], v[184:187], v[192:195], v[34:49]
	ds_read_b64_tr_b16 v[192:193], v209 offset:0x1400
	ds_read_b64_tr_b16 v[194:195], v209 offset:0x1c00
	s_waitcnt lgkmcnt(6)
	v_mfma_f32_32x32x16_bf16 v[34:49], v[230:233], v[234:237], v[34:49]
	ds_read_b64_tr_b16 v[234:235], v209 offset:0x2400
	ds_read_b64_tr_b16 v[236:237], v209 offset:0x2c00
	ds_read_b64_tr_b16 v[238:239], v209 offset:0x3400
	ds_read_b64_tr_b16 v[240:241], v209 offset:0x3c00
	s_waitcnt lgkmcnt(8)
	v_mfma_f32_32x32x16_bf16 v[34:49], v[242:245], v[246:249], v[34:49]
	s_waitcnt lgkmcnt(6)
	v_mfma_f32_32x32x16_bf16 v[18:33], v[178:181], v[188:191], v[18:33]
	ds_read_b64_tr_b16 v[188:189], v209 offset:0x600
	ds_read_b64_tr_b16 v[190:191], v209 offset:0xe00
	s_waitcnt lgkmcnt(6)
	v_mfma_f32_32x32x16_bf16 v[18:33], v[184:187], v[192:195], v[18:33]
	ds_read_b64_tr_b16 v[192:193], v209 offset:0x1600
	ds_read_b64_tr_b16 v[194:195], v209 offset:0x1e00
	s_waitcnt lgkmcnt(6)
	v_mfma_f32_32x32x16_bf16 v[18:33], v[230:233], v[234:237], v[18:33]
	ds_read_b64_tr_b16 v[234:235], v209 offset:0x2600
	ds_read_b64_tr_b16 v[236:237], v209 offset:0x2e00
	ds_read_b64_tr_b16 v[246:247], v209 offset:0x3600
	ds_read_b64_tr_b16 v[248:249], v209 offset:0x3e00
	s_waitcnt lgkmcnt(8)
	v_mfma_f32_32x32x16_bf16 v[18:33], v[242:245], v[238:241], v[18:33]
	s_waitcnt lgkmcnt(6)
	v_mfma_f32_32x32x16_bf16 v[2:17], v[178:181], v[188:191], v[2:17]
	s_cmp_le_i32 s6, s1
	s_cselect_b64 s[6:7], -1, 0
	s_cmp_gt_i32 s38, s8
	s_cselect_b64 s[54:55], -1, 0
	s_and_b64 s[6:7], s[6:7], s[54:55]
	s_and_b64 vcc, exec, s[6:7]
	s_waitcnt lgkmcnt(4)
	v_mfma_f32_32x32x16_bf16 v[2:17], v[184:187], v[192:195], v[2:17]
	s_waitcnt lgkmcnt(2)
	v_mfma_f32_32x32x16_bf16 v[2:17], v[230:233], v[234:237], v[2:17]
	s_waitcnt lgkmcnt(0)
	v_mfma_f32_32x32x16_bf16 v[2:17], v[242:245], v[246:249], v[2:17]
	s_cbranch_vccnz .LBB0_391
	v_subrev_u32_e32 v178, 64, v222
	v_cmp_gt_u32_e32 vcc, s11, v178
	v_add_u32_e32 v178, 0xffffefa0, v222
	s_nop 0
	v_cndmask_b32_e32 v50, v202, v50, vcc
	v_cmp_lt_u32_e32 vcc, s68, v178
	v_add_u32_e32 v178, 0xffffefbf, v222
	s_nop 0
	v_cndmask_b32_e32 v82, v202, v82, vcc
	v_cmp_lt_u32_e32 vcc, s68, v178
	v_add_u32_e32 v178, 0xffffef9f, v222
	s_nop 0
	v_cndmask_b32_e32 v51, v202, v51, vcc
	v_cmp_lt_u32_e32 vcc, s68, v178
	v_add_u32_e32 v178, 0xffffefbe, v222
	s_nop 0
	v_cndmask_b32_e32 v83, v202, v83, vcc
	v_cmp_lt_u32_e32 vcc, s68, v178
	v_add_u32_e32 v178, 0xffffef9e, v222
	s_nop 0
	v_cndmask_b32_e32 v52, v202, v52, vcc
	v_cmp_lt_u32_e32 vcc, s68, v178
	v_add_u32_e32 v178, 0xffffefbd, v222
	s_nop 0
	v_cndmask_b32_e32 v84, v202, v84, vcc
	v_cmp_lt_u32_e32 vcc, s68, v178
	v_add_u32_e32 v178, 0xffffef9d, v222
	s_nop 0
	v_cndmask_b32_e32 v53, v202, v53, vcc
	v_cmp_lt_u32_e32 vcc, s68, v178
	v_add_u32_e32 v178, 0xffffefb8, v222
	s_nop 0
	v_cndmask_b32_e32 v85, v202, v85, vcc
	v_cmp_lt_u32_e32 vcc, s68, v178
	v_add_u32_e32 v178, 0xffffef98, v222
	s_nop 0
	v_cndmask_b32_e32 v54, v202, v54, vcc
	v_cmp_lt_u32_e32 vcc, s68, v178
	v_add_u32_e32 v178, 0xffffefb7, v222
	s_nop 0
	v_cndmask_b32_e32 v86, v202, v86, vcc
	v_cmp_lt_u32_e32 vcc, s68, v178
	v_add_u32_e32 v178, 0xffffef97, v222
	s_nop 0
	v_cndmask_b32_e32 v55, v202, v55, vcc
	v_cmp_lt_u32_e32 vcc, s68, v178
	v_add_u32_e32 v178, 0xffffefb6, v222
	s_nop 0
	v_cndmask_b32_e32 v87, v202, v87, vcc
	v_cmp_lt_u32_e32 vcc, s68, v178
	v_add_u32_e32 v178, 0xffffef96, v222
	s_nop 0
	v_cndmask_b32_e32 v56, v202, v56, vcc
	v_cmp_lt_u32_e32 vcc, s68, v178
	v_add_u32_e32 v178, 0xffffefb5, v222
	s_nop 0
	v_cndmask_b32_e32 v88, v202, v88, vcc
	v_cmp_lt_u32_e32 vcc, s68, v178
	v_add_u32_e32 v178, 0xffffef95, v222
	s_nop 0
	v_cndmask_b32_e32 v57, v202, v57, vcc
	v_cmp_lt_u32_e32 vcc, s68, v178
	v_add_u32_e32 v178, 0xffffefb0, v222
	s_nop 0
	v_cndmask_b32_e32 v89, v202, v89, vcc
	v_cmp_lt_u32_e32 vcc, s68, v178
	v_add_u32_e32 v178, 0xffffef90, v222
	s_nop 0
	v_cndmask_b32_e32 v58, v202, v58, vcc
	v_cmp_lt_u32_e32 vcc, s68, v178
	v_add_u32_e32 v178, 0xffffefaf, v222
	s_nop 0
	v_cndmask_b32_e32 v90, v202, v90, vcc
	v_cmp_lt_u32_e32 vcc, s68, v178
	v_add_u32_e32 v178, 0xffffef8f, v222
	s_nop 0
	v_cndmask_b32_e32 v59, v202, v59, vcc
	v_cmp_lt_u32_e32 vcc, s68, v178
	v_add_u32_e32 v178, 0xffffefae, v222
	s_nop 0
	v_cndmask_b32_e32 v91, v202, v91, vcc
	v_cmp_lt_u32_e32 vcc, s68, v178
	v_add_u32_e32 v178, 0xffffef8e, v222
	s_nop 0
	v_cndmask_b32_e32 v60, v202, v60, vcc
	v_cmp_lt_u32_e32 vcc, s68, v178
	v_add_u32_e32 v178, 0xffffefad, v222
	s_nop 0
	v_cndmask_b32_e32 v92, v202, v92, vcc
	v_cmp_lt_u32_e32 vcc, s68, v178
	v_add_u32_e32 v178, 0xffffef8d, v222
	s_nop 0
	v_cndmask_b32_e32 v61, v202, v61, vcc
	v_cmp_lt_u32_e32 vcc, s68, v178
	v_add_u32_e32 v178, 0xffffefa8, v222
	s_nop 0
	v_cndmask_b32_e32 v93, v202, v93, vcc
	v_cmp_lt_u32_e32 vcc, s68, v178
	v_add_u32_e32 v178, 0xffffef88, v222
	s_nop 0
	v_cndmask_b32_e32 v62, v202, v62, vcc
	v_cmp_lt_u32_e32 vcc, s68, v178
	v_add_u32_e32 v178, 0xffffefa7, v222
	s_nop 0
	v_cndmask_b32_e32 v94, v202, v94, vcc
	v_cmp_lt_u32_e32 vcc, s68, v178
	v_add_u32_e32 v178, 0xffffef87, v222
	s_nop 0
	v_cndmask_b32_e32 v63, v202, v63, vcc
	v_cmp_lt_u32_e32 vcc, s68, v178
	v_add_u32_e32 v178, 0xffffefa6, v222
	s_nop 0
	v_cndmask_b32_e32 v95, v202, v95, vcc
	v_cmp_lt_u32_e32 vcc, s68, v178
	v_add_u32_e32 v178, 0xffffef86, v222
	s_nop 0
	v_cndmask_b32_e32 v64, v202, v64, vcc
	v_cmp_lt_u32_e32 vcc, s68, v178
	v_add_u32_e32 v178, 0xffffefa5, v222
	s_nop 0
	v_cndmask_b32_e32 v96, v202, v96, vcc
	v_cmp_lt_u32_e32 vcc, s68, v178
	v_add_u32_e32 v178, 0xffffef85, v222
	s_nop 0
	v_cndmask_b32_e32 v65, v202, v65, vcc
	v_cmp_lt_u32_e32 vcc, s68, v178
	s_nop 1
	v_cndmask_b32_e32 v97, v202, v97, vcc

.LBB0_395:
	v_cndmask_b32_e64 v226, v178, v182, s[6:7]
	v_mul_f32_e32 v178, 0xbe0293ee, v226
	v_fmamk_f32 v50, v50, 0x3e0293ee, v178
	v_fmamk_f32 v51, v51, 0x3e0293ee, v178
	v_fmamk_f32 v52, v52, 0x3e0293ee, v178
	v_fmamk_f32 v53, v53, 0x3e0293ee, v178
	v_fmamk_f32 v54, v54, 0x3e0293ee, v178
	v_fmamk_f32 v55, v55, 0x3e0293ee, v178
	v_fmamk_f32 v56, v56, 0x3e0293ee, v178
	v_fmamk_f32 v57, v57, 0x3e0293ee, v178
	v_fmamk_f32 v58, v58, 0x3e0293ee, v178
	v_fmamk_f32 v59, v59, 0x3e0293ee, v178
	v_fmamk_f32 v60, v60, 0x3e0293ee, v178
	v_fmamk_f32 v61, v61, 0x3e0293ee, v178
	v_fmamk_f32 v62, v62, 0x3e0293ee, v178
	v_fmamk_f32 v63, v63, 0x3e0293ee, v178
	v_fmamk_f32 v64, v64, 0x3e0293ee, v178
	v_fmamk_f32 v65, v65, 0x3e0293ee, v178
	v_exp_f32_e32 v50, v50
	v_exp_f32_e32 v51, v51
	v_exp_f32_e32 v52, v52
	v_exp_f32_e32 v53, v53
	v_exp_f32_e32 v54, v54
	v_exp_f32_e32 v55, v55
	v_exp_f32_e32 v56, v56
	v_exp_f32_e32 v57, v57
	v_exp_f32_e32 v58, v58
	v_exp_f32_e32 v59, v59
	v_exp_f32_e32 v60, v60
	v_exp_f32_e32 v61, v61
	v_exp_f32_e32 v62, v62
	v_exp_f32_e32 v63, v63
	v_exp_f32_e32 v64, v64
	v_exp_f32_e32 v65, v65
	v_fmamk_f32 v82, v82, 0x3e0293ee, v178
	v_fmamk_f32 v83, v83, 0x3e0293ee, v178
	v_fmamk_f32 v84, v84, 0x3e0293ee, v178
	v_fmamk_f32 v85, v85, 0x3e0293ee, v178
	v_fmamk_f32 v86, v86, 0x3e0293ee, v178
	v_fmamk_f32 v87, v87, 0x3e0293ee, v178
	v_fmamk_f32 v88, v88, 0x3e0293ee, v178
	v_fmamk_f32 v89, v89, 0x3e0293ee, v178
	v_fmamk_f32 v90, v90, 0x3e0293ee, v178
	v_fmamk_f32 v91, v91, 0x3e0293ee, v178
	v_fmamk_f32 v92, v92, 0x3e0293ee, v178
	v_fmamk_f32 v93, v93, 0x3e0293ee, v178
	v_fmamk_f32 v94, v94, 0x3e0293ee, v178
	v_fmamk_f32 v95, v95, 0x3e0293ee, v178
	v_fmamk_f32 v96, v96, 0x3e0293ee, v178
	v_fmac_f32_e32 v178, 0x3e0293ee, v97
	s_waitcnt lgkmcnt(0)
	s_waitcnt vmcnt(0)
	s_barrier
	ds_read_b128 v[230:233], v214 offset:32768
	ds_read_b128 v[234:237], v214 offset:40960
	ds_read_b128 v[238:241], v215 offset:32768
	ds_read_b128 v[242:245], v215 offset:40960
	ds_read_b128 v[180:183], v216 offset:32768
	ds_read_b128 v[184:187], v216 offset:40960
	ds_read_b128 v[246:249], v217 offset:32768
	ds_read_b128 v[250:253], v217 offset:40960
	v_exp_f32_e32 v97, v178
	v_add_f32_e32 v178, 0, v50
	v_add_f32_e32 v178, v51, v178
	s_waitcnt lgkmcnt(7)
	v_mfma_f32_32x32x16_bf16 v[114:129], v[230:233], v[158:161], v[114:129]
	v_add_f32_e32 v178, v52, v178
	v_add_f32_e32 v178, v53, v178
	v_add_f32_e32 v178, v54, v178
	v_add_f32_e32 v178, v55, v178
	v_add_f32_e32 v178, v56, v178
	v_add_f32_e32 v178, v57, v178
	v_add_f32_e32 v178, v58, v178
	s_waitcnt lgkmcnt(6)
	v_mfma_f32_32x32x16_bf16 v[98:113], v[234:237], v[158:161], v[98:113]
	ds_read_b128 v[230:233], v214 offset:32896
	ds_read_b128 v[234:237], v214 offset:41088
	v_add_f32_e32 v178, v59, v178
	v_add_f32_e32 v178, v60, v178
	v_add_f32_e32 v178, v61, v178
	v_exp_f32_e32 v82, v82
	v_add_f32_e32 v178, v62, v178
	v_exp_f32_e32 v83, v83
	s_waitcnt lgkmcnt(7)
	v_mfma_f32_32x32x16_bf16 v[114:129], v[238:241], v[154:157], v[114:129]
	v_add_f32_e32 v178, v63, v178
	v_exp_f32_e32 v84, v84
	v_add_f32_e32 v178, v64, v178
	v_exp_f32_e32 v85, v85
	v_add_f32_e32 v178, v65, v178
	v_exp_f32_e32 v86, v86
	v_add_f32_e32 v178, v82, v178
	s_waitcnt lgkmcnt(6)
	v_mfma_f32_32x32x16_bf16 v[98:113], v[242:245], v[154:157], v[98:113]
	ds_read_b128 v[238:241], v215 offset:32896
	ds_read_b128 v[242:245], v215 offset:41088
	v_exp_f32_e32 v87, v87
	v_add_f32_e32 v178, v83, v178
	v_exp_f32_e32 v88, v88
	v_add_f32_e32 v178, v84, v178
	v_exp_f32_e32 v89, v89
	v_add_f32_e32 v178, v85, v178
	s_waitcnt lgkmcnt(7)
	v_mfma_f32_32x32x16_bf16 v[114:129], v[180:183], v[150:153], v[114:129]
	v_exp_f32_e32 v90, v90
	v_add_f32_e32 v178, v86, v178
	v_exp_f32_e32 v91, v91
	v_add_f32_e32 v178, v87, v178
	v_exp_f32_e32 v92, v92
	v_add_f32_e32 v178, v88, v178
	v_exp_f32_e32 v93, v93
	s_waitcnt lgkmcnt(6)
	v_mfma_f32_32x32x16_bf16 v[98:113], v[184:187], v[150:153], v[98:113]
	ds_read_b128 v[180:183], v216 offset:32896
	ds_read_b128 v[184:187], v216 offset:41088
	v_add_f32_e32 v178, v89, v178
	v_exp_f32_e32 v94, v94
	v_add_f32_e32 v178, v90, v178
	v_exp_f32_e32 v95, v95
	v_add_f32_e32 v178, v91, v178
	v_exp_f32_e32 v96, v96
	s_waitcnt lgkmcnt(7)
	v_mfma_f32_32x32x16_bf16 v[114:129], v[246:249], v[146:149], v[114:129]
	v_add_f32_e32 v178, v92, v178
	v_add_f32_e32 v178, v93, v178
	v_add_f32_e32 v178, v94, v178
	v_add_f32_e32 v178, v95, v178
	v_add_f32_e32 v178, v96, v178
	v_add_f32_e32 v227, v97, v178
	v_mov_b32_e32 v228, v227
	s_waitcnt lgkmcnt(6)
	v_mfma_f32_32x32x16_bf16 v[98:113], v[250:253], v[146:149], v[98:113]
	ds_read_b128 v[246:249], v217 offset:32896
	ds_read_b128 v[250:253], v217 offset:41088
	v_permlane32_swap_b32_e32 v227, v228
	s_waitcnt lgkmcnt(7)
	v_mfma_f32_32x32x16_bf16 v[114:129], v[230:233], v[142:145], v[114:129]
	s_waitcnt lgkmcnt(6)
	v_mfma_f32_32x32x16_bf16 v[98:113], v[234:237], v[142:145], v[98:113]
	s_waitcnt lgkmcnt(5)
	v_mfma_f32_32x32x16_bf16 v[114:129], v[238:241], v[138:141], v[114:129]
	s_waitcnt lgkmcnt(4)
	v_mfma_f32_32x32x16_bf16 v[98:113], v[242:245], v[138:141], v[98:113]
	s_waitcnt lgkmcnt(3)
	v_mfma_f32_32x32x16_bf16 v[114:129], v[180:183], v[134:137], v[114:129]
	s_waitcnt lgkmcnt(2)
	v_mfma_f32_32x32x16_bf16 v[98:113], v[184:187], v[134:137], v[98:113]
	v_cvt_pk_bf16_f32 v178, v50, v51
	v_cvt_pk_bf16_f32 v179, v52, v53
	s_waitcnt lgkmcnt(1)
	v_mfma_f32_32x32x16_bf16 v[114:129], v[246:249], v[130:133], v[114:129]
	v_cvt_pk_bf16_f32 v180, v54, v55
	v_cvt_pk_bf16_f32 v181, v56, v57
	v_cvt_pk_bf16_f32 v182, v58, v59
	v_cvt_pk_bf16_f32 v183, v60, v61
	s_nop 0
	v_permlane32_swap_b32_e32 v178, v180
	s_waitcnt lgkmcnt(0)
	v_mfma_f32_32x32x16_bf16 v[98:113], v[250:253], v[130:133], v[98:113]
	v_cvt_pk_bf16_f32 v184, v62, v63
	v_cvt_pk_bf16_f32 v185, v64, v65
	v_cvt_pk_bf16_f32 v186, v82, v83
	v_cvt_pk_bf16_f32 v187, v84, v85
	v_cvt_pk_bf16_f32 v188, v86, v87
	v_cvt_pk_bf16_f32 v189, v88, v89
	v_cvt_pk_bf16_f32 v190, v90, v91
	v_cvt_pk_bf16_f32 v191, v92, v93
	v_cvt_pk_bf16_f32 v192, v94, v95
	v_cvt_pk_bf16_f32 v193, v96, v97
	v_permlane32_swap_b32_e32 v179, v181
	v_permlane32_swap_b32_e32 v182, v184
	v_permlane32_swap_b32_e32 v183, v185
	v_permlane32_swap_b32_e32 v186, v188
	v_permlane32_swap_b32_e32 v187, v189
	v_permlane32_swap_b32_e32 v190, v192
	v_permlane32_swap_b32_e32 v191, v193
	s_add_i32 m0, s32, 0x0
	v_add_u32_e32 v229, 0x80, v218
	global_load_lds_dwordx4 v218, s[100:101]
	s_add_i32 m0, s32, 0x400
	s_nop 0
	global_load_lds_dwordx4 v229, s[100:101]
	s_sub_u32 s100, s100, 0x4000
	s_subb_u32 s101, s101, 0
	s_add_i32 s6, s33, 1
	s_cmp_lt_i32 s6, s27
	s_cselect_b64 s[54:55], -1, 0
	s_cmp_ge_i32 s6, s27
	s_cbranch_scc1 .LBB0_397
	global_load_dwordx4 v[50:53], v221, s[52:53]
	global_load_dwordx4 v[54:57], v221, s[52:53] offset:32
	global_load_dwordx4 v[82:85], v221, s[52:53] offset:128
	global_load_dwordx4 v[86:89], v221, s[52:53] offset:160
	global_load_dwordx4 v[58:61], v221, s[52:53] offset:64
	global_load_dwordx4 v[62:65], v221, s[52:53] offset:96
	global_load_dwordx4 v[90:93], v221, s[52:53] offset:192
	global_load_dwordx4 v[94:97], v221, s[52:53] offset:224
	s_add_i32 m0, s32, 0xc000
	v_xor_b32_e32 v229, 64, v219
	global_load_lds_dwordx4 v219, s[98:99]
	s_add_i32 m0, s32, 0xc400
	v_add_u32_e32 v229, 0x400, v229
	global_load_lds_dwordx4 v229, s[98:99]
	s_sub_u32 s98, s98, 0x4000
	s_subb_u32 s99, s99, 0

.LBB0_405:
	v_cndmask_b32_e64 v182, v162, v226, s[6:7]
	v_mul_f32_e32 v180, 0xbe0293ee, v182
	v_mov_b32_e32 v183, v180
	v_fmamk_f32 v162, v114, 0x3e0293ee, v180
	v_fmamk_f32 v163, v115, 0x3e0293ee, v180
	v_fmamk_f32 v164, v116, 0x3e0293ee, v180
	v_fmamk_f32 v165, v117, 0x3e0293ee, v180
	v_fmamk_f32 v166, v118, 0x3e0293ee, v180
	v_fmamk_f32 v167, v119, 0x3e0293ee, v180
	v_fmamk_f32 v168, v120, 0x3e0293ee, v180
	v_fmamk_f32 v169, v121, 0x3e0293ee, v180
	v_fmamk_f32 v179, v122, 0x3e0293ee, v180
	v_fmamk_f32 v181, v123, 0x3e0293ee, v180
	v_fmamk_f32 v124, v124, 0x3e0293ee, v180
	v_fmamk_f32 v125, v125, 0x3e0293ee, v180
	v_fmamk_f32 v126, v126, 0x3e0293ee, v180
	v_fmamk_f32 v127, v127, 0x3e0293ee, v180
	v_fmamk_f32 v128, v128, 0x3e0293ee, v180
	v_fmac_f32_e32 v183, 0x3e0293ee, v129
	v_exp_f32_e32 v175, v162
	v_exp_f32_e32 v177, v163
	v_exp_f32_e32 v173, v164
	v_exp_f32_e32 v176, v165
	v_exp_f32_e32 v171, v166
	v_exp_f32_e32 v174, v167
	v_exp_f32_e32 v170, v168
	v_exp_f32_e32 v172, v169
	v_exp_f32_e32 v164, v179
	v_exp_f32_e32 v167, v181
	v_exp_f32_e32 v163, v124
	v_exp_f32_e32 v165, v125
	v_exp_f32_e32 v162, v126
	v_exp_f32_e32 v169, v127
	v_exp_f32_e32 v166, v128
	v_exp_f32_e32 v168, v183
	v_pk_fma_f32 v[128:129], v[98:99], s[16:17], v[180:181] op_sel_hi:[1,0,0]
	v_add_f32_e32 v98, v223, v224
	v_fmac_f32_e32 v98, v220, v213
	v_add_f32_e32 v213, v227, v228
	s_addk_i32 s38, 0xff80
	s_add_i32 s33, s33, 2
	v_pk_fma_f32 v[114:115], v[112:113], s[16:17], v[180:181] op_sel_hi:[1,0,0]
	v_pk_fma_f32 v[116:117], v[110:111], s[16:17], v[180:181] op_sel_hi:[1,0,0]
	v_pk_fma_f32 v[118:119], v[108:109], s[16:17], v[180:181] op_sel_hi:[1,0,0]
	v_pk_fma_f32 v[120:121], v[106:107], s[16:17], v[180:181] op_sel_hi:[1,0,0]
	v_pk_fma_f32 v[122:123], v[104:105], s[16:17], v[180:181] op_sel_hi:[1,0,0]
	v_pk_fma_f32 v[124:125], v[102:103], s[16:17], v[180:181] op_sel_hi:[1,0,0]
	v_pk_fma_f32 v[126:127], v[100:101], s[16:17], v[180:181] op_sel_hi:[1,0,0]
	v_fmac_f32_e32 v213, v98, v225
	v_add_u32_e32 v221, 0xfffffe00, v221
	s_cmp_ge_i32 s33, s27
	v_add_u32_e32 v222, 0x80, v222
	s_waitcnt lgkmcnt(0)
	s_waitcnt vmcnt(0)
	s_barrier
	s_cbranch_scc1 .LBB0_408
	v_mov_b32_e32 v220, v178
	s_branch .LBB0_389
